# baseline (speedup 1.0000x reference)
; __device__ __forceinline__ unsigned cvt_pk_bf16(float lo, float hi) { return __builtin_bit_cast(unsigned, __builtin_amdgcn_cvt_pkrtz(lo, hi)); }
; __device__ __forceinline__ void ssm_proj_load(SsmProj& P, const float* SSB, int g, int fr, int fq) {
; #pragma unroll
;     for (int nt = 0; nt < 8; ++nt) { const int cg = 16 * nt + fr, p = cg >> 1, c = cg & 1; u32x4 w = {0u, 0u, 0u, 0u};
;         if (fq < 2) { const float* s = SSB + ((size_t)g * 64 + p) * 32 + c * 16 + 8 * fq; const f32x4 a = *(const f32x4*)s, b = *(const f32x4*)(s + 4);
;             w = (u32x4){cvt_pk_bf16(a[0], a[1]), cvt_pk_bf16(a[2], a[3]), cvt_pk_bf16(b[0], b[1]), cvt_pk_bf16(b[2], b[3])}; }
;         P.bf[nt] = __builtin_bit_cast(bf16x8, w); }
; }
; __device__ __forceinline__ void phase_ssm2(int wid_s, unsigned char* shm, const float* US, const float* SSA, const float* SSB, const float* FIN, const float* c_re, const float* c_im, const float* dvec, bf16_t* YG) {
;     ...
;         SsmProj P; ssm_proj_load(P, SSB, g, fr, fq);
.LBB0_472:
	s_lshr_b32 s6, s10, 2
	v_and_or_b32 v3, s6, 28, v81
	v_lshl_or_b32 v0, v3, 11, v101
	v_lshlrev_b32_e32 v0, 2, v0
	v_mov_b32_e32 v4, 0
	v_mov_b32_e32 v5, 0
	v_mov_b32_e32 v6, 0
	v_mov_b32_e32 v7, 0
	v_mov_b32_e32 v8, 0
	v_mov_b32_e32 v9, 0
	v_mov_b32_e32 v10, 0
	v_mov_b32_e32 v11, 0
	v_mov_b32_e32 v12, 0
	v_mov_b32_e32 v13, 0
	v_mov_b32_e32 v14, 0
	v_mov_b32_e32 v15, 0
	v_mov_b32_e32 v16, 0
	v_mov_b32_e32 v17, 0
	v_mov_b32_e32 v18, 0
	v_mov_b32_e32 v19, 0
	v_mov_b32_e32 v20, 0
	v_mov_b32_e32 v21, 0
	v_mov_b32_e32 v22, 0
	v_mov_b32_e32 v23, 0
	v_mov_b32_e32 v24, 0
	v_mov_b32_e32 v25, 0
	v_mov_b32_e32 v26, 0
	v_mov_b32_e32 v27, 0
	v_mov_b32_e32 v28, 0
	v_mov_b32_e32 v29, 0
	v_mov_b32_e32 v30, 0
	v_mov_b32_e32 v31, 0
	v_mov_b32_e32 v32, 0
	v_mov_b32_e32 v33, 0
	v_mov_b32_e32 v34, 0
	v_mov_b32_e32 v35, 0
	s_and_saveexec_b64 s[6:7], s[4:5]
	s_cbranch_execz .Lp2_skip
	v_mov_b32_e32 v1, v2
	v_lshl_add_u64 v[126:127], v[82:83], 0, v[0:1]
	v_add_co_u32_e32 v128, vcc, 0x1000, v126
	s_nop 1
	v_addc_co_u32_e32 v129, vcc, 0, v127, vcc
	global_load_dwordx4 v[130:133], v[126:127], off
	global_load_dwordx4 v[134:137], v[126:127], off offset:16
	global_load_dwordx4 v[138:141], v[126:127], off offset:1024
	global_load_dwordx4 v[142:145], v[126:127], off offset:1040
	global_load_dwordx4 v[146:149], v[126:127], off offset:2048
	global_load_dwordx4 v[150:153], v[126:127], off offset:2064
	global_load_dwordx4 v[154:157], v[126:127], off offset:3072
	global_load_dwordx4 v[158:161], v[126:127], off offset:3088
	global_load_dwordx4 v[162:165], v[128:129], off
	global_load_dwordx4 v[166:169], v[128:129], off offset:16
	global_load_dwordx4 v[170:173], v[128:129], off offset:1024
	global_load_dwordx4 v[174:177], v[128:129], off offset:1040
	global_load_dwordx4 v[178:181], v[128:129], off offset:2048
	global_load_dwordx4 v[182:185], v[128:129], off offset:2064
	global_load_dwordx4 v[186:189], v[128:129], off offset:3072
	global_load_dwordx4 v[190:193], v[128:129], off offset:3088
.Lp2_skip:
	s_or_b64 exec, exec, s[6:7]

; __device__ __forceinline__ unsigned cvt_pk_bf16(float lo, float hi) { return __builtin_bit_cast(unsigned, __builtin_amdgcn_cvt_pkrtz(lo, hi)); }
; __device__ __forceinline__ void ssm_proj_load(SsmProj& P, const float* SSB, int g, int fr, int fq) {
; #pragma unroll
;     for (int nt = 0; nt < 8; ++nt) { const int cg = 16 * nt + fr, p = cg >> 1, c = cg & 1; u32x4 w = {0u, 0u, 0u, 0u};
;         if (fq < 2) { const float* s = SSB + ((size_t)g * 64 + p) * 32 + c * 16 + 8 * fq; const f32x4 a = *(const f32x4*)s, b = *(const f32x4*)(s + 4);
;             w = (u32x4){cvt_pk_bf16(a[0], a[1]), cvt_pk_bf16(a[2], a[3]), cvt_pk_bf16(b[0], b[1]), cvt_pk_bf16(b[2], b[3])}; }
;         P.bf[nt] = __builtin_bit_cast(bf16x8, w); }
; __device__ __forceinline__ void phase_ssm2(int wid_s, unsigned char* shm, const float* US, const float* SSA, const float* SSB, const float* FIN, const float* c_re, const float* c_im, const float* dvec, bf16_t* YG) {
;     ...
;             const u32x4 w = {cvt_pk_bf16(cr[0], -ci[0]), cvt_pk_bf16(cr[1], -ci[1]), cvt_pk_bf16(cr[2], -ci[2]), cvt_pk_bf16(cr[3], -ci[3])}; cf[ks] = __builtin_bit_cast(bf16x8, w); }
.LBB0_494:
	s_or_b64 exec, exec, s[6:7]
	v_mov_b32_e32 v105, v2
	v_cvt_pkrtz_f16_f32 v56, v56, -v68
	v_cvt_pkrtz_f16_f32 v57, v57, -v69
	v_cvt_pkrtz_f16_f32 v58, v58, -v70
	v_cvt_pkrtz_f16_f32 v59, v59, -v71
	v_cvt_pkrtz_f16_f32 v52, v52, -v60
	v_cvt_pkrtz_f16_f32 v53, v53, -v61
	v_cvt_pkrtz_f16_f32 v54, v54, -v62
	v_cvt_pkrtz_f16_f32 v55, v55, -v63
	v_cvt_pkrtz_f16_f32 v44, v44, -v64
	v_cvt_pkrtz_f16_f32 v45, v45, -v65
	v_cvt_pkrtz_f16_f32 v46, v46, -v66
	v_cvt_pkrtz_f16_f32 v47, v47, -v67
	v_cvt_pkrtz_f16_f32 v38, v40, -v48
	v_cvt_pkrtz_f16_f32 v39, v41, -v49
	v_cvt_pkrtz_f16_f32 v40, v42, -v50
	v_cvt_pkrtz_f16_f32 v41, v43, -v51
	v_lshl_add_u64 v[0:1], v[88:89], 0, v[104:105]
	v_lshl_add_u64 v[42:43], v[90:91], 0, v[104:105]
	v_lshl_add_u64 v[60:61], v[92:93], 0, v[104:105]
	s_mov_b32 s18, 0
	s_waitcnt vmcnt(0)
	s_and_saveexec_b64 s[6:7], s[4:5]
	v_cvt_pkrtz_f16_f32 v8, v130, v131
	v_cvt_pkrtz_f16_f32 v9, v132, v133
	v_cvt_pkrtz_f16_f32 v10, v134, v135
	v_cvt_pkrtz_f16_f32 v11, v136, v137
	v_cvt_pkrtz_f16_f32 v12, v138, v139
	v_cvt_pkrtz_f16_f32 v13, v140, v141
	v_cvt_pkrtz_f16_f32 v14, v142, v143
	v_cvt_pkrtz_f16_f32 v15, v144, v145
	v_cvt_pkrtz_f16_f32 v4, v146, v147
	v_cvt_pkrtz_f16_f32 v5, v148, v149
	v_cvt_pkrtz_f16_f32 v6, v150, v151
	v_cvt_pkrtz_f16_f32 v7, v152, v153
	v_cvt_pkrtz_f16_f32 v16, v154, v155
	v_cvt_pkrtz_f16_f32 v17, v156, v157
	v_cvt_pkrtz_f16_f32 v18, v158, v159
	v_cvt_pkrtz_f16_f32 v19, v160, v161
	v_cvt_pkrtz_f16_f32 v24, v162, v163
	v_cvt_pkrtz_f16_f32 v25, v164, v165
	v_cvt_pkrtz_f16_f32 v26, v166, v167
	v_cvt_pkrtz_f16_f32 v27, v168, v169
	v_cvt_pkrtz_f16_f32 v28, v170, v171
	v_cvt_pkrtz_f16_f32 v29, v172, v173
	v_cvt_pkrtz_f16_f32 v30, v174, v175
	v_cvt_pkrtz_f16_f32 v31, v176, v177
	v_cvt_pkrtz_f16_f32 v20, v178, v179
	v_cvt_pkrtz_f16_f32 v21, v180, v181
	v_cvt_pkrtz_f16_f32 v22, v182, v183
	v_cvt_pkrtz_f16_f32 v23, v184, v185
	v_cvt_pkrtz_f16_f32 v32, v186, v187
	v_cvt_pkrtz_f16_f32 v33, v188, v189
	v_cvt_pkrtz_f16_f32 v34, v190, v191
	v_cvt_pkrtz_f16_f32 v35, v192, v193
	s_or_b64 exec, exec, s[6:7]
